# RG-LRU conv stage: each tap's third LDS read renamed into a free quad and issued with the first two (12 tap sites), counted lgkmcnt waits adjusted
# speedup vs baseline: 1.0066x; 1.0066x over previous
; #define LAS __attribute__((address_space(3)))
; __device__ __forceinline__ void rglru_task(const Params& P, LAS unsigned char* lds, int b, int n, int qd, int tid, int t0, int t1) {
;     ...
;               for (int j = 0; j < 4; ++j) {
;                   if (prompt || j == 3) {
;                       {
;                           const u32x4 u = prompt ? *(const LAS u32x4*)(rawt + (t + j) * 136 + cc) : *(const u32x4*)(XR + (size_t)(MPR + t) * D + cb0 + cc);
;                           const float x8[8] = {bflo(u.x), bfhi(u.x), bflo(u.y), bfhi(u.y), bflo(u.z), bfhi(u.z), bflo(u.w), bfhi(u.w)};
; #pragma unroll
;                           for (int e = 0; e < 8; ++e) a[e] += x8[e] * cw[j * 128 + cc + e];
;                       }
.LBB0_1313:
	s_andn2_b64 vcc, exec, s[4:5]
	v_add_u32_e32 v209, 0, v207
	s_cbranch_vccnz .LBB0_1315
	v_add_u32_e32 v10, 0x16280, v209
	ds_read_b128 v[12:15], v10
	ds_read_b128 v[210:213], v211
	ds_read_b128 v[240:243], v71
	s_waitcnt lgkmcnt(2)
	v_lshlrev_b32_e32 v10, 16, v12
	v_and_b32_e32 v11, 0xffff0000, v12
	s_waitcnt lgkmcnt(1)
	v_pk_fma_f32 v[10:11], v[210:211], v[10:11], v[4:5]
	v_lshlrev_b32_e32 v4, 16, v13
	v_and_b32_e32 v5, 0xffff0000, v13
	v_pk_fma_f32 v[12:13], v[212:213], v[4:5], v[6:7]
	v_lshlrev_b32_e32 v70, 16, v15
	v_and_b32_e32 v214, 0xffff0000, v15
	v_lshlrev_b32_e32 v210, 16, v14
	v_and_b32_e32 v211, 0xffff0000, v14
	s_waitcnt lgkmcnt(0)
	v_pk_fma_f32 v[14:15], v[240:241], v[210:211], v[0:1]
	v_fma_f32 v70, v242, v70, v2
	v_mul_f32_e32 v210, v243, v214
	v_mov_b64_e32 v[4:5], v[240:241]
	v_mov_b64_e32 v[6:7], v[242:243]

; #define LAS __attribute__((address_space(3)))
; __device__ __forceinline__ void rglru_task(const Params& P, LAS unsigned char* lds, int b, int n, int qd, int tid, int t0, int t1) {
;     ...
;               for (int j = 0; j < 4; ++j) {
;                   if (prompt || j == 3) {
;                       {
;                           const u32x4 u = prompt ? *(const LAS u32x4*)(rawt + (t + j) * 136 + cc) : *(const u32x4*)(XR + (size_t)(MPR + t) * D + cb0 + cc);
;                           const float x8[8] = {bflo(u.x), bfhi(u.x), bflo(u.y), bfhi(u.y), bflo(u.z), bfhi(u.z), bflo(u.w), bfhi(u.w)};
; #pragma unroll
;                           for (int e = 0; e < 8; ++e) a[e] += x8[e] * cw[j * 128 + cc + e];
;                       }
.LBB0_1317:
	s_andn2_b64 vcc, exec, s[4:5]
	s_cbranch_vccnz .LBB0_1319
	v_add_u32_e32 v0, 0x16390, v209
	ds_read_b128 v[214:217], v0
	ds_read_b128 v[218:221], v212
	ds_read_b128 v[240:243], v71
	s_waitcnt lgkmcnt(2)
	v_lshlrev_b32_e32 v0, 16, v214
	v_and_b32_e32 v1, 0xffff0000, v214
	s_waitcnt lgkmcnt(1)
	v_pk_fma_f32 v[6:7], v[218:219], v[0:1], v[10:11]
	v_lshlrev_b32_e32 v0, 16, v215
	v_and_b32_e32 v1, 0xffff0000, v215
	v_pk_fma_f32 v[4:5], v[220:221], v[0:1], v[12:13]
	v_lshlrev_b32_e32 v2, 16, v217
	v_and_b32_e32 v211, 0xffff0000, v217
	v_lshlrev_b32_e32 v0, 16, v216
	v_and_b32_e32 v1, 0xffff0000, v216
	s_waitcnt lgkmcnt(0)
	v_fmac_f32_e32 v70, v242, v2
	v_pk_fma_f32 v[0:1], v[240:241], v[0:1], v[14:15]
	v_mul_f32_e32 v2, v243, v211
	v_mov_b32_e32 v211, v70
	v_mov_b64_e32 v[10:11], v[240:241]
	v_mov_b64_e32 v[12:13], v[242:243]

; #define LAS __attribute__((address_space(3)))
; __device__ __forceinline__ void rglru_task(const Params& P, LAS unsigned char* lds, int b, int n, int qd, int tid, int t0, int t1) {
;     ...
;               for (int j = 0; j < 4; ++j) {
;                   if (prompt || j == 3) {
;                       {
;                           const u32x4 u = prompt ? *(const LAS u32x4*)(rawt + (t + j) * 136 + cc) : *(const u32x4*)(XR + (size_t)(MPR + t) * D + cb0 + cc);
;                           const float x8[8] = {bflo(u.x), bfhi(u.x), bflo(u.y), bfhi(u.y), bflo(u.z), bfhi(u.z), bflo(u.w), bfhi(u.w)};
; #pragma unroll
;                           for (int e = 0; e < 8; ++e) a[e] += x8[e] * cw[j * 128 + cc + e];
;                       }
.LBB0_1328:
	s_andn2_b64 vcc, exec, s[4:5]
	s_cbranch_vccnz .LBB0_1330
	v_add_u32_e32 v10, 0x16290, v209
	ds_read_b128 v[12:15], v10
	ds_read_b128 v[212:215], v212
	ds_read_b128 v[240:243], v71
	s_waitcnt lgkmcnt(2)
	v_lshlrev_b32_e32 v10, 16, v12
	v_and_b32_e32 v11, 0xffff0000, v12
	s_waitcnt lgkmcnt(1)
	v_pk_fma_f32 v[10:11], v[212:213], v[10:11], v[4:5]
	v_lshlrev_b32_e32 v4, 16, v13
	v_and_b32_e32 v5, 0xffff0000, v13
	v_pk_fma_f32 v[12:13], v[214:215], v[4:5], v[6:7]
	v_lshlrev_b32_e32 v70, 16, v15
	v_and_b32_e32 v211, 0xffff0000, v15
	v_lshlrev_b32_e32 v212, 16, v14
	v_and_b32_e32 v213, 0xffff0000, v14
	s_waitcnt lgkmcnt(0)
	v_pk_fma_f32 v[14:15], v[240:241], v[212:213], v[0:1]
	v_fma_f32 v70, v242, v70, v2
	v_mul_f32_e32 v211, v243, v211
	v_mov_b64_e32 v[4:5], v[240:241]
	v_mov_b64_e32 v[6:7], v[242:243]

; #define LAS __attribute__((address_space(3)))
; __device__ __forceinline__ void rglru_task(const Params& P, LAS unsigned char* lds, int b, int n, int qd, int tid, int t0, int t1) {
;     ...
;               for (int j = 0; j < 4; ++j) {
;                   if (prompt || j == 3) {
;                       {
;                           const u32x4 u = prompt ? *(const LAS u32x4*)(rawt + (t + j) * 136 + cc) : *(const u32x4*)(XR + (size_t)(MPR + t) * D + cb0 + cc);
;                           const float x8[8] = {bflo(u.x), bfhi(u.x), bflo(u.y), bfhi(u.y), bflo(u.z), bfhi(u.z), bflo(u.w), bfhi(u.w)};
; #pragma unroll
;                           for (int e = 0; e < 8; ++e) a[e] += x8[e] * cw[j * 128 + cc + e];
;                       }
.LBB0_1332:
	s_andn2_b64 vcc, exec, s[4:5]
	s_cbranch_vccnz .LBB0_1334
	s_waitcnt lgkmcnt(0)
	v_add_u32_e32 v0, 0x163a0, v209
	ds_read_b128 v[214:217], v0
	ds_read_b128 v[218:221], v213
	ds_read_b128 v[240:243], v71
	s_waitcnt lgkmcnt(2)
	v_lshlrev_b32_e32 v0, 16, v214
	v_and_b32_e32 v1, 0xffff0000, v214
	s_waitcnt lgkmcnt(1)
	v_pk_fma_f32 v[6:7], v[218:219], v[0:1], v[10:11]
	v_lshlrev_b32_e32 v0, 16, v215
	v_and_b32_e32 v1, 0xffff0000, v215
	v_pk_fma_f32 v[4:5], v[220:221], v[0:1], v[12:13]
	v_lshlrev_b32_e32 v2, 16, v217
	v_and_b32_e32 v212, 0xffff0000, v217
	v_lshlrev_b32_e32 v0, 16, v216
	v_and_b32_e32 v1, 0xffff0000, v216
	s_waitcnt lgkmcnt(0)
	v_fmac_f32_e32 v70, v242, v2
	v_pk_fma_f32 v[0:1], v[240:241], v[0:1], v[14:15]
	v_mul_f32_e32 v2, v243, v212
	v_mov_b32_e32 v212, v70
	v_mov_b64_e32 v[10:11], v[240:241]
	v_mov_b64_e32 v[12:13], v[242:243]

; #define LAS __attribute__((address_space(3)))
; __device__ __forceinline__ void rglru_task(const Params& P, LAS unsigned char* lds, int b, int n, int qd, int tid, int t0, int t1) {
;     ...
;               for (int j = 0; j < 4; ++j) {
;                   if (prompt || j == 3) {
;                       {
;                           const u32x4 u = prompt ? *(const LAS u32x4*)(rawt + (t + j) * 136 + cc) : *(const u32x4*)(XR + (size_t)(MPR + t) * D + cb0 + cc);
;                           const float x8[8] = {bflo(u.x), bfhi(u.x), bflo(u.y), bfhi(u.y), bflo(u.z), bfhi(u.z), bflo(u.w), bfhi(u.w)};
; #pragma unroll
;                           for (int e = 0; e < 8; ++e) a[e] += x8[e] * cw[j * 128 + cc + e];
;                       }
.LBB0_1342:
	v_add_u32_e32 v10, 0x164a0, v209
	ds_read_b128 v[214:217], v10
	ds_read_b128 v[218:221], v212
	ds_read_b128 v[240:243], v13
	s_waitcnt lgkmcnt(2)
	v_lshlrev_b32_e32 v10, 16, v214
	v_and_b32_e32 v11, 0xffff0000, v214
	s_waitcnt lgkmcnt(1)
	v_pk_fma_f32 v[70:71], v[218:219], v[10:11], v[6:7]
	v_lshlrev_b32_e32 v6, 16, v215
	v_and_b32_e32 v7, 0xffff0000, v215
	v_pk_fma_f32 v[14:15], v[220:221], v[6:7], v[4:5]
	v_lshlrev_b32_e32 v12, 16, v217
	v_and_b32_e32 v213, 0xffff0000, v217
	v_lshlrev_b32_e32 v10, 16, v216
	v_and_b32_e32 v11, 0xffff0000, v216
	s_waitcnt lgkmcnt(0)
	v_fmac_f32_e32 v211, v242, v12
	v_pk_fma_f32 v[10:11], v[240:241], v[10:11], v[0:1]
	v_mul_f32_e32 v213, v243, v213
	v_mov_b32_e32 v12, v211
	s_and_b64 vcc, exec, s[52:53]
	s_mov_b64 s[4:5], -1
	v_mov_b64_e32 v[4:5], v[240:241]
	v_mov_b64_e32 v[6:7], v[242:243]
	s_cbranch_vccnz .LBB0_1322

; #define LAS __attribute__((address_space(3)))
; __device__ __forceinline__ void rglru_task(const Params& P, LAS unsigned char* lds, int b, int n, int qd, int tid, int t0, int t1) {
;     ...
;               for (int j = 0; j < 4; ++j) {
;                   if (prompt || j == 3) {
;                       {
;                           const u32x4 u = prompt ? *(const LAS u32x4*)(rawt + (t + j) * 136 + cc) : *(const u32x4*)(XR + (size_t)(MPR + t) * D + cb0 + cc);
;                           const float x8[8] = {bflo(u.x), bfhi(u.x), bflo(u.y), bfhi(u.y), bflo(u.z), bfhi(u.z), bflo(u.w), bfhi(u.w)};
; #pragma unroll
;                           for (int e = 0; e < 8; ++e) a[e] += x8[e] * cw[j * 128 + cc + e];
;                       }
.LBB0_1345:
	v_add_u32_e32 v10, 0x164b0, v209
	ds_read_b128 v[214:217], v10
	ds_read_b128 v[218:221], v213
	ds_read_b128 v[240:243], v13
	s_waitcnt lgkmcnt(2)
	v_lshlrev_b32_e32 v10, 16, v214
	v_and_b32_e32 v11, 0xffff0000, v214
	s_waitcnt lgkmcnt(1)
	v_pk_fma_f32 v[70:71], v[218:219], v[10:11], v[6:7]
	v_lshlrev_b32_e32 v6, 16, v215
	v_and_b32_e32 v7, 0xffff0000, v215
	v_pk_fma_f32 v[14:15], v[220:221], v[6:7], v[4:5]
	v_lshlrev_b32_e32 v12, 16, v217
	v_and_b32_e32 v217, 0xffff0000, v217
	v_lshlrev_b32_e32 v10, 16, v216
	v_and_b32_e32 v11, 0xffff0000, v216
	s_waitcnt lgkmcnt(0)
	v_fmac_f32_e32 v212, v242, v12
	v_pk_fma_f32 v[10:11], v[240:241], v[10:11], v[0:1]
	v_mul_f32_e32 v214, v243, v217
	v_mov_b32_e32 v12, v212
	s_and_b64 vcc, exec, s[52:53]
	s_mov_b64 s[4:5], -1
	v_mov_b64_e32 v[4:5], v[240:241]
	v_mov_b64_e32 v[6:7], v[242:243]
	s_cbranch_vccnz .LBB0_1337

; #define LAS __attribute__((address_space(3)))
; __device__ __forceinline__ void rglru_task(const Params& P, LAS unsigned char* lds, int b, int n, int qd, int tid, int t0, int t1) {
;     ...
;               for (int j = 0; j < 4; ++j) {
;                   if (prompt || j == 3) {
;                       {
;                           const u32x4 u = prompt ? *(const LAS u32x4*)(rawt + (t + j) * 136 + cc) : *(const u32x4*)(XR + (size_t)(MPR + t) * D + cb0 + cc);
;                           const float x8[8] = {bflo(u.x), bfhi(u.x), bflo(u.y), bfhi(u.y), bflo(u.z), bfhi(u.z), bflo(u.w), bfhi(u.w)};
; #pragma unroll
;                           for (int e = 0; e < 8; ++e) a[e] += x8[e] * cw[j * 128 + cc + e];
;                       }
.LBB0_1520:
	s_andn2_b64 vcc, exec, s[4:5]
	v_add_u32_e32 v217, 0, v215
	s_cbranch_vccnz .LBB0_1522
	v_add_u32_e32 v10, 0x16280, v217
	ds_read_b128 v[12:15], v10
	ds_read_b128 v[218:221], v219
	ds_read_b128 v[240:243], v19
	s_waitcnt lgkmcnt(2)
	v_lshlrev_b32_e32 v10, 16, v12
	v_and_b32_e32 v11, 0xffff0000, v12
	s_waitcnt lgkmcnt(1)
	v_pk_fma_f32 v[10:11], v[218:219], v[10:11], v[4:5]
	v_lshlrev_b32_e32 v4, 16, v13
	v_and_b32_e32 v5, 0xffff0000, v13
	v_pk_fma_f32 v[12:13], v[220:221], v[4:5], v[6:7]
	v_lshlrev_b32_e32 v18, 16, v15
	v_and_b32_e32 v222, 0xffff0000, v15
	v_lshlrev_b32_e32 v218, 16, v14
	v_and_b32_e32 v219, 0xffff0000, v14
	s_waitcnt lgkmcnt(0)
	v_pk_fma_f32 v[14:15], v[240:241], v[218:219], v[0:1]
	v_fma_f32 v18, v242, v18, v2
	v_mul_f32_e32 v218, v243, v222
	v_mov_b64_e32 v[4:5], v[240:241]
	v_mov_b64_e32 v[6:7], v[242:243]

; #define LAS __attribute__((address_space(3)))
; __device__ __forceinline__ void rglru_task(const Params& P, LAS unsigned char* lds, int b, int n, int qd, int tid, int t0, int t1) {
;     ...
;               for (int j = 0; j < 4; ++j) {
;                   if (prompt || j == 3) {
;                       {
;                           const u32x4 u = prompt ? *(const LAS u32x4*)(rawt + (t + j) * 136 + cc) : *(const u32x4*)(XR + (size_t)(MPR + t) * D + cb0 + cc);
;                           const float x8[8] = {bflo(u.x), bfhi(u.x), bflo(u.y), bfhi(u.y), bflo(u.z), bfhi(u.z), bflo(u.w), bfhi(u.w)};
; #pragma unroll
;                           for (int e = 0; e < 8; ++e) a[e] += x8[e] * cw[j * 128 + cc + e];
;                       }
.LBB0_1524:
	s_andn2_b64 vcc, exec, s[4:5]
	s_cbranch_vccnz .LBB0_1526
	v_add_u32_e32 v0, 0x16390, v217
	ds_read_b128 v[222:225], v0
	ds_read_b128 v[226:229], v220
	ds_read_b128 v[240:243], v19
	s_waitcnt lgkmcnt(2)
	v_lshlrev_b32_e32 v0, 16, v222
	v_and_b32_e32 v1, 0xffff0000, v222
	s_waitcnt lgkmcnt(1)
	v_pk_fma_f32 v[6:7], v[226:227], v[0:1], v[10:11]
	v_lshlrev_b32_e32 v0, 16, v223
	v_and_b32_e32 v1, 0xffff0000, v223
	v_pk_fma_f32 v[4:5], v[228:229], v[0:1], v[12:13]
	v_lshlrev_b32_e32 v2, 16, v225
	v_and_b32_e32 v219, 0xffff0000, v225
	v_lshlrev_b32_e32 v0, 16, v224
	v_and_b32_e32 v1, 0xffff0000, v224
	s_waitcnt lgkmcnt(0)
	v_fmac_f32_e32 v18, v242, v2
	v_pk_fma_f32 v[0:1], v[240:241], v[0:1], v[14:15]
	v_mul_f32_e32 v2, v243, v219
	v_mov_b32_e32 v219, v18
	v_mov_b64_e32 v[10:11], v[240:241]
	v_mov_b64_e32 v[12:13], v[242:243]

; #define LAS __attribute__((address_space(3)))
; __device__ __forceinline__ void rglru_task(const Params& P, LAS unsigned char* lds, int b, int n, int qd, int tid, int t0, int t1) {
;     ...
;               for (int j = 0; j < 4; ++j) {
;                   if (prompt || j == 3) {
;                       {
;                           const u32x4 u = prompt ? *(const LAS u32x4*)(rawt + (t + j) * 136 + cc) : *(const u32x4*)(XR + (size_t)(MPR + t) * D + cb0 + cc);
;                           const float x8[8] = {bflo(u.x), bfhi(u.x), bflo(u.y), bfhi(u.y), bflo(u.z), bfhi(u.z), bflo(u.w), bfhi(u.w)};
; #pragma unroll
;                           for (int e = 0; e < 8; ++e) a[e] += x8[e] * cw[j * 128 + cc + e];
;                       }
.LBB0_1535:
	s_andn2_b64 vcc, exec, s[4:5]
	s_cbranch_vccnz .LBB0_1537
	v_add_u32_e32 v10, 0x16290, v217
	ds_read_b128 v[12:15], v10
	ds_read_b128 v[220:223], v220
	ds_read_b128 v[240:243], v19
	s_waitcnt lgkmcnt(2)
	v_lshlrev_b32_e32 v10, 16, v12
	v_and_b32_e32 v11, 0xffff0000, v12
	s_waitcnt lgkmcnt(1)
	v_pk_fma_f32 v[10:11], v[220:221], v[10:11], v[4:5]
	v_lshlrev_b32_e32 v4, 16, v13
	v_and_b32_e32 v5, 0xffff0000, v13
	v_pk_fma_f32 v[12:13], v[222:223], v[4:5], v[6:7]
	v_lshlrev_b32_e32 v18, 16, v15
	v_and_b32_e32 v219, 0xffff0000, v15
	v_lshlrev_b32_e32 v220, 16, v14
	v_and_b32_e32 v221, 0xffff0000, v14
	s_waitcnt lgkmcnt(0)
	v_pk_fma_f32 v[14:15], v[240:241], v[220:221], v[0:1]
	v_fma_f32 v18, v242, v18, v2
	v_mul_f32_e32 v219, v243, v219
	v_mov_b64_e32 v[4:5], v[240:241]
	v_mov_b64_e32 v[6:7], v[242:243]

; #define LAS __attribute__((address_space(3)))
; __device__ __forceinline__ void rglru_task(const Params& P, LAS unsigned char* lds, int b, int n, int qd, int tid, int t0, int t1) {
;     ...
;               for (int j = 0; j < 4; ++j) {
;                   if (prompt || j == 3) {
;                       {
;                           const u32x4 u = prompt ? *(const LAS u32x4*)(rawt + (t + j) * 136 + cc) : *(const u32x4*)(XR + (size_t)(MPR + t) * D + cb0 + cc);
;                           const float x8[8] = {bflo(u.x), bfhi(u.x), bflo(u.y), bfhi(u.y), bflo(u.z), bfhi(u.z), bflo(u.w), bfhi(u.w)};
; #pragma unroll
;                           for (int e = 0; e < 8; ++e) a[e] += x8[e] * cw[j * 128 + cc + e];
;                       }
.LBB0_1539:
	s_andn2_b64 vcc, exec, s[4:5]
	s_cbranch_vccnz .LBB0_1541
	s_waitcnt lgkmcnt(0)
	v_add_u32_e32 v0, 0x163a0, v217
	ds_read_b128 v[222:225], v0
	ds_read_b128 v[226:229], v221
	ds_read_b128 v[240:243], v19
	s_waitcnt lgkmcnt(2)
	v_lshlrev_b32_e32 v0, 16, v222
	v_and_b32_e32 v1, 0xffff0000, v222
	s_waitcnt lgkmcnt(1)
	v_pk_fma_f32 v[6:7], v[226:227], v[0:1], v[10:11]
	v_lshlrev_b32_e32 v0, 16, v223
	v_and_b32_e32 v1, 0xffff0000, v223
	v_pk_fma_f32 v[4:5], v[228:229], v[0:1], v[12:13]
	v_lshlrev_b32_e32 v2, 16, v225
	v_and_b32_e32 v220, 0xffff0000, v225
	v_lshlrev_b32_e32 v0, 16, v224
	v_and_b32_e32 v1, 0xffff0000, v224
	s_waitcnt lgkmcnt(0)
	v_fmac_f32_e32 v18, v242, v2
	v_pk_fma_f32 v[0:1], v[240:241], v[0:1], v[14:15]
	v_mul_f32_e32 v2, v243, v220
	v_mov_b32_e32 v220, v18
	v_mov_b64_e32 v[10:11], v[240:241]
	v_mov_b64_e32 v[12:13], v[242:243]

; #define LAS __attribute__((address_space(3)))
; __device__ __forceinline__ void rglru_task(const Params& P, LAS unsigned char* lds, int b, int n, int qd, int tid, int t0, int t1) {
;     ...
;               for (int j = 0; j < 4; ++j) {
;                   if (prompt || j == 3) {
;                       {
;                           const u32x4 u = prompt ? *(const LAS u32x4*)(rawt + (t + j) * 136 + cc) : *(const u32x4*)(XR + (size_t)(MPR + t) * D + cb0 + cc);
;                           const float x8[8] = {bflo(u.x), bfhi(u.x), bflo(u.y), bfhi(u.y), bflo(u.z), bfhi(u.z), bflo(u.w), bfhi(u.w)};
; #pragma unroll
;                           for (int e = 0; e < 8; ++e) a[e] += x8[e] * cw[j * 128 + cc + e];
;                       }
.LBB0_1549:
	v_add_u32_e32 v10, 0x164a0, v217
	ds_read_b128 v[222:225], v10
	ds_read_b128 v[226:229], v220
	ds_read_b128 v[240:243], v13
	s_waitcnt lgkmcnt(2)
	v_lshlrev_b32_e32 v10, 16, v222
	v_and_b32_e32 v11, 0xffff0000, v222
	s_waitcnt lgkmcnt(1)
	v_pk_fma_f32 v[18:19], v[226:227], v[10:11], v[6:7]
	v_lshlrev_b32_e32 v6, 16, v223
	v_and_b32_e32 v7, 0xffff0000, v223
	v_pk_fma_f32 v[14:15], v[228:229], v[6:7], v[4:5]
	v_lshlrev_b32_e32 v12, 16, v225
	v_and_b32_e32 v221, 0xffff0000, v225
	v_lshlrev_b32_e32 v10, 16, v224
	v_and_b32_e32 v11, 0xffff0000, v224
	s_waitcnt lgkmcnt(0)
	v_fmac_f32_e32 v219, v242, v12
	v_pk_fma_f32 v[10:11], v[240:241], v[10:11], v[0:1]
	v_mul_f32_e32 v221, v243, v221
	v_mov_b32_e32 v12, v219
	s_and_b64 vcc, exec, s[52:53]
	s_mov_b64 s[4:5], -1
	v_mov_b64_e32 v[4:5], v[240:241]
	v_mov_b64_e32 v[6:7], v[242:243]
	s_cbranch_vccnz .LBB0_1529

; #define LAS __attribute__((address_space(3)))
; __device__ __forceinline__ void rglru_task(const Params& P, LAS unsigned char* lds, int b, int n, int qd, int tid, int t0, int t1) {
;     ...
;               for (int j = 0; j < 4; ++j) {
;                   if (prompt || j == 3) {
;                       {
;                           const u32x4 u = prompt ? *(const LAS u32x4*)(rawt + (t + j) * 136 + cc) : *(const u32x4*)(XR + (size_t)(MPR + t) * D + cb0 + cc);
;                           const float x8[8] = {bflo(u.x), bfhi(u.x), bflo(u.y), bfhi(u.y), bflo(u.z), bfhi(u.z), bflo(u.w), bfhi(u.w)};
; #pragma unroll
;                           for (int e = 0; e < 8; ++e) a[e] += x8[e] * cw[j * 128 + cc + e];
;                       }
.LBB0_1552:
	v_add_u32_e32 v10, 0x164b0, v217
	ds_read_b128 v[222:225], v10
	ds_read_b128 v[226:229], v221
	ds_read_b128 v[240:243], v13
	s_waitcnt lgkmcnt(2)
	v_lshlrev_b32_e32 v10, 16, v222
	v_and_b32_e32 v11, 0xffff0000, v222
	s_waitcnt lgkmcnt(1)
	v_pk_fma_f32 v[18:19], v[226:227], v[10:11], v[6:7]
	v_lshlrev_b32_e32 v6, 16, v223
	v_and_b32_e32 v7, 0xffff0000, v223
	v_pk_fma_f32 v[14:15], v[228:229], v[6:7], v[4:5]
	v_lshlrev_b32_e32 v12, 16, v225
	v_and_b32_e32 v225, 0xffff0000, v225
	v_lshlrev_b32_e32 v10, 16, v224
	v_and_b32_e32 v11, 0xffff0000, v224
	s_waitcnt lgkmcnt(0)
	v_fmac_f32_e32 v220, v242, v12
	v_pk_fma_f32 v[10:11], v[240:241], v[10:11], v[0:1]
	v_mul_f32_e32 v222, v243, v225
	v_mov_b32_e32 v12, v220
	s_and_b64 vcc, exec, s[52:53]
	s_mov_b64 s[4:5], -1
	v_mov_b64_e32 v[4:5], v[240:241]
	v_mov_b64_e32 v[6:7], v[242:243]
	s_cbranch_vccnz .LBB0_1544
